# stagger 50us
# speedup vs baseline: 1.0130x; 1.0024x over previous
; __global__ void __launch_bounds__(NWAVES * 64, 2) hybrid_fwd(Args args) {
;     ...
;     if (IN(1)) {
;         pg8::Gemm g{Hb, (const bf16*)(ws + WS_WGU1), M, 2 * FF, D}; pg8::StaticOrder S; S.init(M, 2 * FF, G, (int)blockIdx.x);
;         pg8::EpiSwiGLU<false> E{ACT, FF, nullptr};
;         pg8::gemm_phase<pg8::EpiSwiGLU<false>, pg8::StaticOrder, true, true>(lds, g, S, E);
.Lstag0_loop:
	s_sleep 8
	s_memrealtime s[2:3]
	s_waitcnt lgkmcnt(0)
	s_sub_u32 s2, s2, s4
	s_cmp_lt_u32 s2, 5000
	s_cbranch_scc1 .Lstag0_loop
